# attention epilogue: 16-channel group pairs exchanged with v_permlane16_swap, dwordx4 stores (8 -> 4 store instructions per wave-item)
# baseline (speedup 1.0000x reference)
.LBB0_201:
	v_bfe_u32 v210, v220, 4, 1
	v_mul_u32_u24_e32 v210, 24, v210
	v_mov_b32_e32 v211, 0
	v_and_b32_e32 v1, 64, v220
	v_xor_b32_e32 v0, 16, v220
	v_add_u32_e32 v1, 64, v1
	v_cmp_lt_i32_e32 vcc, v0, v1
	v_readlane_b32 s0, v255, 31
	v_readlane_b32 s70, v254, 6
	v_cndmask_b32_e32 v0, v220, v0, vcc
	s_waitcnt vmcnt(0)
	v_lshlrev_b32_e32 v44, 2, v0
	v_xor_b32_e32 v0, 32, v220
	v_cmp_lt_i32_e32 vcc, v0, v1
	v_or_b32_e32 v42, s0, v165
	v_readlane_b32 s0, v255, 32
	v_cndmask_b32_e32 v0, v220, v0, vcc
	v_lshlrev_b32_e32 v3, 2, v0
	ds_bpermute_b32 v0, v44, v138
	v_lshl_or_b32 v8, v166, 2, s0
	v_readlane_b32 s71, v254, 7
	s_movk_i32 s77, 0x1c00
	v_ashrrev_i32_e32 v43, 31, v42
	s_waitcnt lgkmcnt(0)
	v_add_f32_e32 v0, v138, v0
	ds_bpermute_b32 v1, v3, v0
	v_readlane_b32 s34, v255, 29
	v_readlane_b32 s68, v254, 5
	v_readlane_b32 s69, v254, 8
	v_readlane_b32 s72, v254, 9
	s_waitcnt lgkmcnt(0)
	v_add_f32_e32 v0, v0, v1
	v_div_scale_f32 v1, s[0:1], v0, v0, 1.0
	v_rcp_f32_e32 v2, v1
	v_readlane_b32 s73, v254, 10
	v_readlane_b32 s74, v254, 11
	v_readlane_b32 s75, v254, 12
	v_fma_f32 v4, -v1, v2, 1.0
	v_fmac_f32_e32 v2, v4, v2
	v_div_scale_f32 v4, vcc, 1.0, v0, 1.0
	v_mul_f32_e32 v5, v4, v2
	v_fma_f32 v6, -v1, v5, v4
	v_fmac_f32_e32 v5, v6, v2
	v_fma_f32 v1, -v1, v5, v4
	v_div_fmas_f32 v1, v1, v2, v5
	v_div_fixup_f32 v2, v1, v0, 1.0
	v_mov_b64_e32 v[0:1], s[70:71]
	v_mad_i64_i32 v[0:1], s[0:1], v42, s77, v[0:1]
	s_mov_b64 s[0:1], 0x1000
	s_nop 0
	v_lshl_add_u64 v[6:7], v[0:1], 0, s[0:1]
	v_lshlrev_b32_e32 v4, 1, v8
	v_mov_b32_e32 v5, v9
	v_lshl_add_u64 v[46:47], v[6:7], 0, v[4:5]
	v_mov_b64_e32 v[176:177], v[46:47]
	global_load_dwordx2 v[46:47], v[46:47], off
	global_load_dwordx2 v[178:179], v[176:177], off offset:32
	global_load_dwordx2 v[180:181], v[176:177], off offset:64
	global_load_dwordx2 v[182:183], v[176:177], off offset:96
	v_lshlrev_b64 v[0:1], 11, v[42:43]
	v_readlane_b32 s0, v251, 10
	v_readlane_b32 s1, v251, 11
	v_readlane_b32 s2, v251, 12
	v_readlane_b32 s3, v251, 13
	s_mov_b64 s[0:1], 0xb00200
	v_pk_mul_f32 v[38:39], v[38:39], v[2:3] op_sel_hi:[1,0]
	v_lshl_add_u64 v[0:1], s[2:3], 0, v[0:1]
	v_lshl_add_u64 v[0:1], v[0:1], 0, s[0:1]
	v_pk_mul_f32 v[40:41], v[40:41], v[2:3] op_sel_hi:[1,0]
	v_lshl_add_u64 v[4:5], v[0:1], 0, v[4:5]
	v_pk_mul_f32 v[34:35], v[34:35], v[2:3] op_sel_hi:[1,0]
	v_pk_mul_f32 v[36:37], v[36:37], v[2:3] op_sel_hi:[1,0]
	v_pk_mul_f32 v[30:31], v[30:31], v[2:3] op_sel_hi:[1,0]
	v_pk_mul_f32 v[32:33], v[32:33], v[2:3] op_sel_hi:[1,0]
	v_pk_mul_f32 v[26:27], v[26:27], v[2:3] op_sel_hi:[1,0]
	v_pk_mul_f32 v[28:29], v[28:29], v[2:3] op_sel_hi:[1,0]
	v_readlane_b32 s76, v254, 13
	v_readlane_b32 s35, v255, 30
	s_waitcnt vmcnt(3)
	v_lshlrev_b32_e32 v43, 16, v46
	v_and_b32_e32 v45, 0xffff0000, v46
	v_mul_f32_e32 v46, 0xbfb8aa3b, v43
	v_exp_f32_e32 v48, v46
	v_mul_f32_e32 v46, 0xbfb8aa3b, v45
	v_exp_f32_e32 v49, v46
	s_nop 0
	v_pk_add_f32 v[48:49], v[48:49], 1.0 op_sel_hi:[1,0]
	s_nop 0
	v_div_scale_f32 v46, s[0:1], v49, v49, v45
	v_rcp_f32_e32 v50, v46
	s_nop 0
	v_fma_f32 v51, -v46, v50, 1.0
	v_fmac_f32_e32 v50, v51, v50
	v_div_scale_f32 v51, vcc, v45, v49, v45
	v_mul_f32_e32 v52, v51, v50
	v_fma_f32 v53, -v46, v52, v51
	v_fmac_f32_e32 v52, v53, v50
	v_fma_f32 v46, -v46, v52, v51
	v_div_fmas_f32 v46, v46, v50, v52
	v_div_fixup_f32 v49, v46, v49, v45
	v_div_scale_f32 v45, s[0:1], v48, v48, v43
	v_rcp_f32_e32 v46, v45
	s_nop 0
	v_fma_f32 v50, -v45, v46, 1.0
	v_fmac_f32_e32 v46, v50, v46
	v_div_scale_f32 v50, vcc, v43, v48, v43
	v_mul_f32_e32 v51, v50, v46
	v_fma_f32 v52, -v45, v51, v50
	v_fmac_f32_e32 v51, v52, v46
	v_fma_f32 v45, -v45, v51, v50
	v_div_fmas_f32 v45, v45, v46, v51
	v_div_fixup_f32 v48, v45, v48, v43
	v_lshlrev_b32_e32 v43, 16, v47
	v_and_b32_e32 v45, 0xffff0000, v47
	v_mul_f32_e32 v46, 0xbfb8aa3b, v43
	v_mul_f32_e32 v47, 0xbfb8aa3b, v45
	v_exp_f32_e32 v46, v46
	v_exp_f32_e32 v47, v47
	v_pk_mul_f32 v[38:39], v[38:39], v[48:49]
	v_pk_add_f32 v[46:47], v[46:47], 1.0 op_sel_hi:[1,0]
	s_nop 0
	v_div_scale_f32 v48, s[0:1], v47, v47, v45
	v_rcp_f32_e32 v49, v48
	v_cvt_pk_bf16_f32 v38, v38, v39
	v_fma_f32 v50, -v48, v49, 1.0
	v_fmac_f32_e32 v49, v50, v49
	v_div_scale_f32 v50, vcc, v45, v47, v45
	v_mul_f32_e32 v51, v50, v49
	v_fma_f32 v52, -v48, v51, v50
	v_fmac_f32_e32 v51, v52, v49
	v_fma_f32 v48, -v48, v51, v50
	v_div_fmas_f32 v48, v48, v49, v51
	v_div_fixup_f32 v47, v48, v47, v45
	v_div_scale_f32 v45, s[0:1], v46, v46, v43
	v_rcp_f32_e32 v48, v45
	s_nop 0
	v_fma_f32 v49, -v45, v48, 1.0
	v_fmac_f32_e32 v48, v49, v48
	v_div_scale_f32 v49, vcc, v43, v46, v43
	v_mul_f32_e32 v50, v49, v48
	v_fma_f32 v51, -v45, v50, v49
	v_fmac_f32_e32 v50, v51, v48
	v_fma_f32 v45, -v45, v50, v49
	v_div_fmas_f32 v45, v45, v48, v50
	v_div_fixup_f32 v46, v45, v46, v43
	v_pk_mul_f32 v[40:41], v[40:41], v[46:47]
	s_nop 0
	v_cvt_pk_bf16_f32 v39, v40, v41
	v_mov_b64_e32 v[204:205], v[38:39]
	v_lshl_add_u64 v[208:209], v[4:5], 0, v[210:211]
	v_or_b32_e32 v38, 16, v8
	v_lshlrev_b32_e32 v4, 1, v38
	v_mov_b32_e32 v5, v9
	v_lshl_add_u64 v[40:41], v[6:7], 0, v[4:5]
	s_waitcnt vmcnt(2)
	v_mov_b64_e32 v[40:41], v[178:179]
	v_lshl_add_u64 v[4:5], v[0:1], 0, v[4:5]
	v_mov_b32_e32 v39, v9
	s_nop 0
	v_lshlrev_b32_e32 v43, 16, v40
	v_and_b32_e32 v40, 0xffff0000, v40
	v_mul_f32_e32 v45, 0xbfb8aa3b, v43
	v_exp_f32_e32 v46, v45
	v_mul_f32_e32 v45, 0xbfb8aa3b, v40
	v_exp_f32_e32 v47, v45
	s_nop 0
	v_pk_add_f32 v[46:47], v[46:47], 1.0 op_sel_hi:[1,0]
	s_nop 0
	v_div_scale_f32 v45, s[0:1], v47, v47, v40
	v_rcp_f32_e32 v48, v45
	s_nop 0
	v_fma_f32 v49, -v45, v48, 1.0
	v_fmac_f32_e32 v48, v49, v48
	v_div_scale_f32 v49, vcc, v40, v47, v40
	v_mul_f32_e32 v50, v49, v48
	v_fma_f32 v51, -v45, v50, v49
	v_fmac_f32_e32 v50, v51, v48
	v_fma_f32 v45, -v45, v50, v49
	v_div_fmas_f32 v45, v45, v48, v50
	v_div_fixup_f32 v47, v45, v47, v40
	v_div_scale_f32 v40, s[0:1], v46, v46, v43
	v_rcp_f32_e32 v45, v40
	s_nop 0
	v_fma_f32 v48, -v40, v45, 1.0
	v_fmac_f32_e32 v45, v48, v45
	v_div_scale_f32 v48, vcc, v43, v46, v43
	v_mul_f32_e32 v49, v48, v45
	v_fma_f32 v50, -v40, v49, v48
	v_fmac_f32_e32 v49, v50, v45
	v_fma_f32 v40, -v40, v49, v48
	v_div_fmas_f32 v40, v40, v45, v49
	v_div_fixup_f32 v46, v40, v46, v43
	v_lshlrev_b32_e32 v43, 16, v41
	v_and_b32_e32 v45, 0xffff0000, v41
	v_mul_f32_e32 v40, 0xbfb8aa3b, v43
	v_mul_f32_e32 v41, 0xbfb8aa3b, v45
	v_exp_f32_e32 v40, v40
	v_exp_f32_e32 v41, v41
	v_pk_mul_f32 v[34:35], v[34:35], v[46:47]
	v_pk_add_f32 v[40:41], v[40:41], 1.0 op_sel_hi:[1,0]
	s_nop 0
	v_div_scale_f32 v46, s[0:1], v41, v41, v45
	v_rcp_f32_e32 v47, v46
	v_cvt_pk_bf16_f32 v34, v34, v35
	v_fma_f32 v48, -v46, v47, 1.0
	v_fmac_f32_e32 v47, v48, v47
	v_div_scale_f32 v48, vcc, v45, v41, v45
	v_mul_f32_e32 v49, v48, v47
	v_fma_f32 v50, -v46, v49, v48
	v_fmac_f32_e32 v49, v50, v47
	v_fma_f32 v46, -v46, v49, v48
	v_div_fmas_f32 v46, v46, v47, v49
	v_div_fixup_f32 v41, v46, v41, v45
	v_div_scale_f32 v45, s[0:1], v40, v40, v43
	v_rcp_f32_e32 v46, v45
	s_nop 0
	v_fma_f32 v47, -v45, v46, 1.0
	v_fmac_f32_e32 v46, v47, v46
	v_div_scale_f32 v47, vcc, v43, v40, v43
	v_mul_f32_e32 v48, v47, v46
	v_fma_f32 v49, -v45, v48, v47
	v_fmac_f32_e32 v48, v49, v46
	v_fma_f32 v45, -v45, v48, v47
	v_div_fmas_f32 v45, v45, v46, v48
	v_div_fixup_f32 v40, v45, v40, v43
	v_pk_mul_f32 v[36:37], v[36:37], v[40:41]
	s_nop 0
	v_cvt_pk_bf16_f32 v35, v36, v37
	v_mov_b64_e32 v[206:207], v[34:35]
	s_nop 1
	v_permlane16_swap_b32_e32 v204, v206
	v_permlane16_swap_b32_e32 v205, v207
	global_store_dwordx4 v[208:209], v[204:207], off
	v_or_b32_e32 v34, 32, v8
	v_lshlrev_b32_e32 v4, 1, v34
	v_mov_b32_e32 v5, v9
	v_lshl_add_u64 v[36:37], v[6:7], 0, v[4:5]
	s_waitcnt vmcnt(2)
	v_mov_b64_e32 v[36:37], v[180:181]
	v_lshl_add_u64 v[4:5], v[0:1], 0, v[4:5]
	v_mov_b32_e32 v35, v9
	s_nop 0
	v_lshlrev_b32_e32 v43, 16, v36
	v_and_b32_e32 v36, 0xffff0000, v36
	v_mul_f32_e32 v40, 0xbfb8aa3b, v43
	v_mul_f32_e32 v41, 0xbfb8aa3b, v36
	v_exp_f32_e32 v40, v40
	v_exp_f32_e32 v41, v41
	s_nop 0
	v_pk_add_f32 v[40:41], v[40:41], 1.0 op_sel_hi:[1,0]
	s_nop 0
	v_div_scale_f32 v45, s[0:1], v41, v41, v36
	v_rcp_f32_e32 v46, v45
	s_nop 0
	v_fma_f32 v47, -v45, v46, 1.0
	v_fmac_f32_e32 v46, v47, v46
	v_div_scale_f32 v47, vcc, v36, v41, v36
	v_mul_f32_e32 v48, v47, v46
	v_fma_f32 v49, -v45, v48, v47
	v_fmac_f32_e32 v48, v49, v46
	v_fma_f32 v45, -v45, v48, v47
	v_div_fmas_f32 v45, v45, v46, v48
	v_div_fixup_f32 v41, v45, v41, v36
	v_div_scale_f32 v36, s[0:1], v40, v40, v43
	v_rcp_f32_e32 v45, v36
	s_nop 0
	v_fma_f32 v46, -v36, v45, 1.0
	v_fmac_f32_e32 v45, v46, v45
	v_div_scale_f32 v46, vcc, v43, v40, v43
	v_mul_f32_e32 v47, v46, v45
	v_fma_f32 v48, -v36, v47, v46
	v_fmac_f32_e32 v47, v48, v45
	v_fma_f32 v36, -v36, v47, v46
	v_div_fmas_f32 v36, v36, v45, v47
	v_div_fixup_f32 v40, v36, v40, v43
	v_pk_mul_f32 v[30:31], v[30:31], v[40:41]
	v_lshlrev_b32_e32 v40, 16, v37
	v_and_b32_e32 v41, 0xffff0000, v37
	v_mul_f32_e32 v36, 0xbfb8aa3b, v40
	v_mul_f32_e32 v37, 0xbfb8aa3b, v41
	v_exp_f32_e32 v36, v36
	v_exp_f32_e32 v37, v37
	v_cvt_pk_bf16_f32 v30, v30, v31
	v_pk_add_f32 v[36:37], v[36:37], 1.0 op_sel_hi:[1,0]
	s_nop 0
	v_div_scale_f32 v43, s[0:1], v37, v37, v41
	v_rcp_f32_e32 v45, v43
	s_nop 0
	v_fma_f32 v46, -v43, v45, 1.0
	v_fmac_f32_e32 v45, v46, v45
	v_div_scale_f32 v46, vcc, v41, v37, v41
	v_mul_f32_e32 v47, v46, v45
	v_fma_f32 v48, -v43, v47, v46
	v_fmac_f32_e32 v47, v48, v45
	v_fma_f32 v43, -v43, v47, v46
	v_div_fmas_f32 v43, v43, v45, v47
	v_div_fixup_f32 v37, v43, v37, v41
	v_div_scale_f32 v41, s[0:1], v36, v36, v40
	v_rcp_f32_e32 v43, v41
	s_nop 0
	v_fma_f32 v45, -v41, v43, 1.0
	v_fmac_f32_e32 v43, v45, v43
	v_div_scale_f32 v45, vcc, v40, v36, v40
	v_mul_f32_e32 v46, v45, v43
	v_fma_f32 v47, -v41, v46, v45
	v_fmac_f32_e32 v46, v47, v43
	v_fma_f32 v41, -v41, v46, v45
	v_div_fmas_f32 v41, v41, v43, v46
	v_div_fixup_f32 v36, v41, v36, v40
	v_pk_mul_f32 v[32:33], v[32:33], v[36:37]
	s_nop 0
	v_cvt_pk_bf16_f32 v31, v32, v33
	v_mov_b64_e32 v[212:213], v[30:31]
	v_lshl_add_u64 v[216:217], v[4:5], 0, v[210:211]
	v_or_b32_e32 v4, 48, v8
	v_lshlrev_b32_e32 v30, 1, v4
	v_mov_b32_e32 v31, v9
	v_lshl_add_u64 v[6:7], v[6:7], 0, v[30:31]
	s_waitcnt vmcnt(1)
	v_mov_b64_e32 v[6:7], v[182:183]
	v_lshl_add_u64 v[0:1], v[0:1], 0, v[30:31]
	v_mov_b32_e32 v5, v9
	s_nop 0
	v_lshlrev_b32_e32 v36, 16, v6
	v_and_b32_e32 v6, 0xffff0000, v6
	v_mul_f32_e32 v32, 0xbfb8aa3b, v36
	v_mul_f32_e32 v33, 0xbfb8aa3b, v6
	v_exp_f32_e32 v32, v32
	v_exp_f32_e32 v33, v33
	s_nop 0
	v_pk_add_f32 v[32:33], v[32:33], 1.0 op_sel_hi:[1,0]
	s_nop 0
	v_div_scale_f32 v37, s[0:1], v33, v33, v6
	v_rcp_f32_e32 v40, v37
	s_nop 0
	v_fma_f32 v41, -v37, v40, 1.0
	v_fmac_f32_e32 v40, v41, v40
	v_div_scale_f32 v41, vcc, v6, v33, v6
	v_mul_f32_e32 v43, v41, v40
	v_fma_f32 v45, -v37, v43, v41
	v_fmac_f32_e32 v43, v45, v40
	v_fma_f32 v37, -v37, v43, v41
	v_div_fmas_f32 v37, v37, v40, v43
	v_div_fixup_f32 v33, v37, v33, v6
	v_div_scale_f32 v6, s[0:1], v32, v32, v36
	v_rcp_f32_e32 v37, v6
	s_nop 0
	v_fma_f32 v40, -v6, v37, 1.0
	v_fmac_f32_e32 v37, v40, v37
	v_div_scale_f32 v40, vcc, v36, v32, v36
	v_mul_f32_e32 v41, v40, v37
	v_fma_f32 v43, -v6, v41, v40
	v_fmac_f32_e32 v41, v43, v37
	v_fma_f32 v6, -v6, v41, v40
	v_div_fmas_f32 v6, v6, v37, v41
	v_div_fixup_f32 v32, v6, v32, v36
	v_pk_mul_f32 v[26:27], v[26:27], v[32:33]
	v_lshlrev_b32_e32 v32, 16, v7
	v_and_b32_e32 v33, 0xffff0000, v7
	v_mul_f32_e32 v6, 0xbfb8aa3b, v32
	v_mul_f32_e32 v2, 0xbfb8aa3b, v33
	v_exp_f32_e32 v6, v6
	v_exp_f32_e32 v7, v2
	v_cvt_pk_bf16_f32 v26, v26, v27
	v_pk_add_f32 v[6:7], v[6:7], 1.0 op_sel_hi:[1,0]
	s_nop 0
	v_div_scale_f32 v2, s[0:1], v7, v7, v33
	v_rcp_f32_e32 v36, v2
	s_nop 0
	v_fma_f32 v37, -v2, v36, 1.0
	v_fmac_f32_e32 v36, v37, v36
	v_div_scale_f32 v37, vcc, v33, v7, v33
	v_mul_f32_e32 v40, v37, v36
	v_fma_f32 v41, -v2, v40, v37
	v_fmac_f32_e32 v40, v41, v36
	v_fma_f32 v2, -v2, v40, v37
	v_div_fmas_f32 v2, v2, v36, v40
	v_div_fixup_f32 v7, v2, v7, v33
	v_div_scale_f32 v2, s[0:1], v6, v6, v32
	v_rcp_f32_e32 v33, v2
	s_nop 0
	v_fma_f32 v36, -v2, v33, 1.0
	v_fmac_f32_e32 v33, v36, v33
	v_div_scale_f32 v36, vcc, v32, v6, v32
	v_mul_f32_e32 v37, v36, v33
	v_fma_f32 v40, -v2, v37, v36
	v_fmac_f32_e32 v37, v40, v33
	v_fma_f32 v2, -v2, v37, v36
	v_div_fmas_f32 v2, v2, v33, v37
	v_div_fixup_f32 v6, v2, v6, v32
	v_pk_mul_f32 v[6:7], v[28:29], v[6:7]
	v_mov_b64_e32 v[36:37], v[8:9]
	v_cvt_pk_bf16_f32 v27, v6, v7
	v_mov_b64_e32 v[214:215], v[26:27]
	s_nop 1
	v_permlane16_swap_b32_e32 v212, v214
	v_permlane16_swap_b32_e32 v213, v215
	global_store_dwordx4 v[216:217], v[212:215], off
	ds_bpermute_b32 v0, v44, v139
	s_waitcnt lgkmcnt(0)
	v_add_f32_e32 v0, v139, v0
	ds_bpermute_b32 v1, v3, v0
.LBB0_202:
	v_bfe_u32 v210, v220, 4, 1
	v_mul_u32_u24_e32 v210, 24, v210
	v_mov_b32_e32 v211, 0
	s_waitcnt lgkmcnt(0)
	v_add_f32_e32 v0, v0, v1
	v_div_scale_f32 v1, s[0:1], v0, v0, 1.0
	v_rcp_f32_e32 v2, v1
	v_readlane_b32 s0, v251, 10
	v_readlane_b32 s2, v251, 12
	v_readlane_b32 s3, v251, 13
	v_fma_f32 v3, -v1, v2, 1.0
	v_fmac_f32_e32 v2, v3, v2
	v_div_scale_f32 v3, vcc, 1.0, v0, 1.0
	v_mul_f32_e32 v6, v3, v2
	v_fma_f32 v7, -v1, v6, v3
	v_fmac_f32_e32 v6, v7, v2
	v_fma_f32 v1, -v1, v6, v3
	v_div_fmas_f32 v1, v1, v2, v6
	v_div_fixup_f32 v2, v1, v0, 1.0
	v_or_b32_e32 v3, 16, v42
	v_readlane_b32 s1, v251, 11
	v_mov_b64_e32 v[0:1], s[2:3]
	v_mad_i64_i32 v[0:1], s[0:1], v3, s77, v[0:1]
	s_mov_b64 s[0:1], 0x4f01000
	s_nop 0
	v_lshl_add_u64 v[6:7], v[0:1], 0, s[0:1]
	v_lshlrev_b64 v[26:27], 1, v[36:37]
	v_lshl_add_u64 v[28:29], v[6:7], 0, v[26:27]
	v_mov_b64_e32 v[176:177], v[28:29]
	global_load_dwordx2 v[28:29], v[28:29], off
	global_load_dwordx2 v[178:179], v[176:177], off offset:32
	global_load_dwordx2 v[180:181], v[176:177], off offset:64
	global_load_dwordx2 v[182:183], v[176:177], off offset:96
	s_movk_i32 s0, 0xec00
	v_mad_i64_i32 v[0:1], s[0:1], v3, s0, v[0:1]
	s_mov_b64 s[0:1], 0xb00200
	s_nop 0
	v_lshl_add_u64 v[0:1], v[0:1], 0, s[0:1]
	v_lshlrev_b64 v[4:5], 1, v[4:5]
	s_waitcnt vmcnt(3)
	v_lshlrev_b32_e32 v3, 16, v28
	v_and_b32_e32 v8, 0xffff0000, v28
	v_mul_f32_e32 v28, 0xbfb8aa3b, v3
	v_exp_f32_e32 v30, v28
	v_mul_f32_e32 v28, 0xbfb8aa3b, v8
	v_exp_f32_e32 v31, v28
	v_pk_mul_f32 v[22:23], v[2:3], v[22:23] op_sel_hi:[0,1]
	v_pk_add_f32 v[30:31], v[30:31], 1.0 op_sel_hi:[1,0]
	s_nop 0
	v_div_scale_f32 v28, s[0:1], v31, v31, v8
	v_rcp_f32_e32 v32, v28
	s_nop 0
	v_fma_f32 v33, -v28, v32, 1.0
	v_fmac_f32_e32 v32, v33, v32
	v_div_scale_f32 v33, vcc, v8, v31, v8
	v_mul_f32_e32 v36, v33, v32
	v_fma_f32 v37, -v28, v36, v33
	v_fmac_f32_e32 v36, v37, v32
	v_fma_f32 v28, -v28, v36, v33
	v_div_fmas_f32 v28, v28, v32, v36
	v_div_fixup_f32 v31, v28, v31, v8
	v_div_scale_f32 v8, s[0:1], v30, v30, v3
	v_rcp_f32_e32 v28, v8
	s_nop 0
	v_fma_f32 v32, -v8, v28, 1.0
	v_fmac_f32_e32 v28, v32, v28
	v_div_scale_f32 v32, vcc, v3, v30, v3
	v_mul_f32_e32 v33, v32, v28
	v_fma_f32 v36, -v8, v33, v32
	v_fmac_f32_e32 v33, v36, v28
	v_fma_f32 v8, -v8, v33, v32
	v_div_fmas_f32 v8, v8, v28, v33
	v_div_fixup_f32 v30, v8, v30, v3
	v_lshlrev_b32_e32 v3, 16, v29
	v_and_b32_e32 v8, 0xffff0000, v29
	v_mul_f32_e32 v28, 0xbfb8aa3b, v3
	v_mul_f32_e32 v29, 0xbfb8aa3b, v8
	v_exp_f32_e32 v28, v28
	v_exp_f32_e32 v29, v29
	v_pk_mul_f32 v[22:23], v[22:23], v[30:31]
	v_pk_mul_f32 v[24:25], v[2:3], v[24:25] op_sel_hi:[0,1]
	v_cvt_pk_bf16_f32 v22, v22, v23
	v_pk_add_f32 v[28:29], v[28:29], 1.0 op_sel_hi:[1,0]
	s_nop 0
	v_div_scale_f32 v30, s[0:1], v29, v29, v8
	v_rcp_f32_e32 v31, v30
	s_nop 0
	v_fma_f32 v32, -v30, v31, 1.0
	v_fmac_f32_e32 v31, v32, v31
	v_div_scale_f32 v32, vcc, v8, v29, v8
	v_mul_f32_e32 v33, v32, v31
	v_fma_f32 v36, -v30, v33, v32
	v_fmac_f32_e32 v33, v36, v31
	v_fma_f32 v30, -v30, v33, v32
	v_div_fmas_f32 v30, v30, v31, v33
	v_div_fixup_f32 v29, v30, v29, v8
	v_div_scale_f32 v8, s[0:1], v28, v28, v3
	v_rcp_f32_e32 v30, v8
	s_nop 0
	v_fma_f32 v31, -v8, v30, 1.0
	v_fmac_f32_e32 v30, v31, v30
	v_div_scale_f32 v31, vcc, v3, v28, v3
	v_mul_f32_e32 v32, v31, v30
	v_fma_f32 v33, -v8, v32, v31
	v_fmac_f32_e32 v32, v33, v30
	v_fma_f32 v8, -v8, v32, v31
	v_div_fmas_f32 v8, v8, v30, v32
	v_div_fixup_f32 v28, v8, v28, v3
	v_pk_mul_f32 v[24:25], v[24:25], v[28:29]
	s_nop 0
	v_cvt_pk_bf16_f32 v23, v24, v25
	v_lshl_add_u64 v[24:25], v[0:1], 0, v[26:27]
	v_mov_b64_e32 v[204:205], v[22:23]
	v_lshl_add_u64 v[208:209], v[24:25], 0, v[210:211]
	v_lshlrev_b64 v[22:23], 1, v[38:39]
	v_lshl_add_u64 v[24:25], v[6:7], 0, v[22:23]
	s_waitcnt vmcnt(2)
	v_mov_b64_e32 v[24:25], v[178:179]
	s_nop 0
	v_lshlrev_b32_e32 v3, 16, v24
	v_and_b32_e32 v8, 0xffff0000, v24
	v_mul_f32_e32 v24, 0xbfb8aa3b, v3
	v_exp_f32_e32 v26, v24
	v_mul_f32_e32 v24, 0xbfb8aa3b, v8
	v_exp_f32_e32 v27, v24
	v_pk_mul_f32 v[18:19], v[2:3], v[18:19] op_sel_hi:[0,1]
	v_pk_add_f32 v[26:27], v[26:27], 1.0 op_sel_hi:[1,0]
	s_nop 0
	v_div_scale_f32 v24, s[0:1], v27, v27, v8
	v_rcp_f32_e32 v28, v24
	s_nop 0
	v_fma_f32 v29, -v24, v28, 1.0
	v_fmac_f32_e32 v28, v29, v28
	v_div_scale_f32 v29, vcc, v8, v27, v8
	v_mul_f32_e32 v30, v29, v28
	v_fma_f32 v31, -v24, v30, v29
	v_fmac_f32_e32 v30, v31, v28
	v_fma_f32 v24, -v24, v30, v29
	v_div_fmas_f32 v24, v24, v28, v30
	v_div_fixup_f32 v27, v24, v27, v8
	v_div_scale_f32 v8, s[0:1], v26, v26, v3
	v_rcp_f32_e32 v24, v8
	s_nop 0
	v_fma_f32 v28, -v8, v24, 1.0
	v_fmac_f32_e32 v24, v28, v24
	v_div_scale_f32 v28, vcc, v3, v26, v3
	v_mul_f32_e32 v29, v28, v24
	v_fma_f32 v30, -v8, v29, v28
	v_fmac_f32_e32 v29, v30, v24
	v_fma_f32 v8, -v8, v29, v28
	v_div_fmas_f32 v8, v8, v24, v29
	v_div_fixup_f32 v26, v8, v26, v3
	v_lshlrev_b32_e32 v3, 16, v25
	v_and_b32_e32 v8, 0xffff0000, v25
	v_mul_f32_e32 v24, 0xbfb8aa3b, v3
	v_mul_f32_e32 v25, 0xbfb8aa3b, v8
	v_exp_f32_e32 v24, v24
	v_exp_f32_e32 v25, v25
	v_pk_mul_f32 v[18:19], v[18:19], v[26:27]
	v_pk_mul_f32 v[20:21], v[2:3], v[20:21] op_sel_hi:[0,1]
	v_cvt_pk_bf16_f32 v18, v18, v19
	v_pk_add_f32 v[24:25], v[24:25], 1.0 op_sel_hi:[1,0]
	s_nop 0
	v_div_scale_f32 v26, s[0:1], v25, v25, v8
	v_rcp_f32_e32 v27, v26
	s_nop 0
	v_fma_f32 v28, -v26, v27, 1.0
	v_fmac_f32_e32 v27, v28, v27
	v_div_scale_f32 v28, vcc, v8, v25, v8
	v_mul_f32_e32 v29, v28, v27
	v_fma_f32 v30, -v26, v29, v28
	v_fmac_f32_e32 v29, v30, v27
	v_fma_f32 v26, -v26, v29, v28
	v_div_fmas_f32 v26, v26, v27, v29
	v_div_fixup_f32 v25, v26, v25, v8
	v_div_scale_f32 v8, s[0:1], v24, v24, v3
	v_rcp_f32_e32 v26, v8
	s_nop 0
	v_fma_f32 v27, -v8, v26, 1.0
	v_fmac_f32_e32 v26, v27, v26
	v_div_scale_f32 v27, vcc, v3, v24, v3
	v_mul_f32_e32 v28, v27, v26
	v_fma_f32 v29, -v8, v28, v27
	v_fmac_f32_e32 v28, v29, v26
	v_fma_f32 v8, -v8, v28, v27
	v_div_fmas_f32 v8, v8, v26, v28
	v_div_fixup_f32 v24, v8, v24, v3
	v_pk_mul_f32 v[20:21], v[20:21], v[24:25]
	s_nop 0
	v_cvt_pk_bf16_f32 v19, v20, v21
	v_lshl_add_u64 v[20:21], v[0:1], 0, v[22:23]
	v_mov_b64_e32 v[206:207], v[18:19]
	s_nop 1
	v_permlane16_swap_b32_e32 v204, v206
	v_permlane16_swap_b32_e32 v205, v207
	global_store_dwordx4 v[208:209], v[204:207], off
	v_lshlrev_b64 v[18:19], 1, v[34:35]
	v_lshl_add_u64 v[20:21], v[6:7], 0, v[18:19]
	s_waitcnt vmcnt(2)
	v_mov_b64_e32 v[20:21], v[180:181]
	v_lshl_add_u64 v[6:7], v[6:7], 0, v[4:5]
	s_nop 0
	v_lshlrev_b32_e32 v3, 16, v20
	v_and_b32_e32 v8, 0xffff0000, v20
	v_mul_f32_e32 v20, 0xbfb8aa3b, v3
	v_exp_f32_e32 v22, v20
	v_mul_f32_e32 v20, 0xbfb8aa3b, v8
	v_exp_f32_e32 v23, v20
	v_pk_mul_f32 v[14:15], v[2:3], v[14:15] op_sel_hi:[0,1]
	v_pk_add_f32 v[22:23], v[22:23], 1.0 op_sel_hi:[1,0]
	s_nop 0
	v_div_scale_f32 v20, s[0:1], v23, v23, v8
	v_rcp_f32_e32 v24, v20
	s_nop 0
	v_fma_f32 v25, -v20, v24, 1.0
	v_fmac_f32_e32 v24, v25, v24
	v_div_scale_f32 v25, vcc, v8, v23, v8
	v_mul_f32_e32 v26, v25, v24
	v_fma_f32 v27, -v20, v26, v25
	v_fmac_f32_e32 v26, v27, v24
	v_fma_f32 v20, -v20, v26, v25
	v_div_fmas_f32 v20, v20, v24, v26
	v_div_fixup_f32 v23, v20, v23, v8
	v_div_scale_f32 v8, s[0:1], v22, v22, v3
	v_rcp_f32_e32 v20, v8
	s_nop 0
	v_fma_f32 v24, -v8, v20, 1.0
	v_fmac_f32_e32 v20, v24, v20
	v_div_scale_f32 v24, vcc, v3, v22, v3
	v_mul_f32_e32 v25, v24, v20
	v_fma_f32 v26, -v8, v25, v24
	v_fmac_f32_e32 v25, v26, v20
	v_fma_f32 v8, -v8, v25, v24
	v_div_fmas_f32 v8, v8, v20, v25
	v_div_fixup_f32 v22, v8, v22, v3
	v_lshlrev_b32_e32 v3, 16, v21
	v_and_b32_e32 v8, 0xffff0000, v21
	v_mul_f32_e32 v20, 0xbfb8aa3b, v3
	v_mul_f32_e32 v21, 0xbfb8aa3b, v8
	v_exp_f32_e32 v20, v20
	v_exp_f32_e32 v21, v21
	v_pk_mul_f32 v[14:15], v[14:15], v[22:23]
	v_pk_mul_f32 v[16:17], v[2:3], v[16:17] op_sel_hi:[0,1]
	v_cvt_pk_bf16_f32 v14, v14, v15
	v_pk_add_f32 v[20:21], v[20:21], 1.0 op_sel_hi:[1,0]
	s_nop 0
	v_div_scale_f32 v22, s[0:1], v21, v21, v8
	v_rcp_f32_e32 v23, v22
	s_nop 0
	v_fma_f32 v24, -v22, v23, 1.0
	v_fmac_f32_e32 v23, v24, v23
	v_div_scale_f32 v24, vcc, v8, v21, v8
	v_mul_f32_e32 v25, v24, v23
	v_fma_f32 v26, -v22, v25, v24
	v_fmac_f32_e32 v25, v26, v23
	v_fma_f32 v22, -v22, v25, v24
	v_div_fmas_f32 v22, v22, v23, v25
	v_div_fixup_f32 v21, v22, v21, v8
	v_div_scale_f32 v8, s[0:1], v20, v20, v3
	v_rcp_f32_e32 v22, v8
	s_nop 0
	v_fma_f32 v23, -v8, v22, 1.0
	v_fmac_f32_e32 v22, v23, v22
	v_div_scale_f32 v23, vcc, v3, v20, v3
	v_mul_f32_e32 v24, v23, v22
	v_fma_f32 v25, -v8, v24, v23
	v_fmac_f32_e32 v24, v25, v22
	v_fma_f32 v8, -v8, v24, v23
	v_div_fmas_f32 v8, v8, v22, v24
	v_div_fixup_f32 v20, v8, v20, v3
	v_pk_mul_f32 v[16:17], v[16:17], v[20:21]
	s_nop 0
	v_cvt_pk_bf16_f32 v15, v16, v17
	v_lshl_add_u64 v[16:17], v[0:1], 0, v[18:19]
	v_mov_b64_e32 v[212:213], v[14:15]
	v_lshl_add_u64 v[216:217], v[16:17], 0, v[210:211]
	s_waitcnt vmcnt(1)
	v_mov_b64_e32 v[14:15], v[182:183]
	v_lshl_add_u64 v[0:1], v[0:1], 0, v[4:5]
	s_nop 0
	v_lshlrev_b32_e32 v3, 16, v14
	v_and_b32_e32 v8, 0xffff0000, v14
	v_mul_f32_e32 v6, 0xbfb8aa3b, v3
	v_mul_f32_e32 v7, 0xbfb8aa3b, v8
	v_exp_f32_e32 v6, v6
	v_exp_f32_e32 v7, v7
	v_pk_mul_f32 v[10:11], v[2:3], v[10:11] op_sel_hi:[0,1]
	v_pk_add_f32 v[6:7], v[6:7], 1.0 op_sel_hi:[1,0]
	s_nop 0
	v_div_scale_f32 v14, s[0:1], v7, v7, v8
	v_rcp_f32_e32 v16, v14
	s_nop 0
	v_fma_f32 v17, -v14, v16, 1.0
	v_fmac_f32_e32 v16, v17, v16
	v_div_scale_f32 v17, vcc, v8, v7, v8
	v_mul_f32_e32 v18, v17, v16
	v_fma_f32 v19, -v14, v18, v17
	v_fmac_f32_e32 v18, v19, v16
	v_fma_f32 v14, -v14, v18, v17
	v_div_fmas_f32 v14, v14, v16, v18
	v_div_fixup_f32 v7, v14, v7, v8
	v_div_scale_f32 v8, s[0:1], v6, v6, v3
	v_rcp_f32_e32 v14, v8
	s_nop 0
	v_fma_f32 v16, -v8, v14, 1.0
	v_fmac_f32_e32 v14, v16, v14
	v_div_scale_f32 v16, vcc, v3, v6, v3
	v_mul_f32_e32 v17, v16, v14
	v_fma_f32 v18, -v8, v17, v16
	v_fmac_f32_e32 v17, v18, v14
	v_fma_f32 v8, -v8, v17, v16
	v_div_fmas_f32 v8, v8, v14, v17
	v_div_fixup_f32 v6, v8, v6, v3
	v_lshlrev_b32_e32 v8, 16, v15
	v_and_b32_e32 v14, 0xffff0000, v15
	v_pk_mul_f32 v[6:7], v[10:11], v[6:7]
	v_mul_f32_e32 v3, 0xbfb8aa3b, v8
	v_mul_f32_e32 v11, 0xbfb8aa3b, v14
	v_exp_f32_e32 v10, v3
	v_exp_f32_e32 v11, v11
	v_pk_mul_f32 v[2:3], v[2:3], v[12:13] op_sel_hi:[0,1]
	v_cvt_pk_bf16_f32 v6, v6, v7
	v_pk_add_f32 v[10:11], v[10:11], 1.0 op_sel_hi:[1,0]
	s_nop 0
	v_div_scale_f32 v12, s[0:1], v11, v11, v14
	v_rcp_f32_e32 v13, v12
	s_nop 0
	v_fma_f32 v15, -v12, v13, 1.0
	v_fmac_f32_e32 v13, v15, v13
	v_div_scale_f32 v15, vcc, v14, v11, v14
	v_mul_f32_e32 v16, v15, v13
	v_fma_f32 v17, -v12, v16, v15
	v_fmac_f32_e32 v16, v17, v13
	v_fma_f32 v12, -v12, v16, v15
	v_div_fmas_f32 v12, v12, v13, v16
	v_div_fixup_f32 v11, v12, v11, v14
	v_div_scale_f32 v12, s[0:1], v10, v10, v8
	v_rcp_f32_e32 v13, v12
	s_nop 0
	v_fma_f32 v14, -v12, v13, 1.0
	v_fmac_f32_e32 v13, v14, v13
	v_div_scale_f32 v14, vcc, v8, v10, v8
	v_mul_f32_e32 v15, v14, v13
	v_fma_f32 v16, -v12, v15, v14
	v_fmac_f32_e32 v15, v16, v13
	v_fma_f32 v12, -v12, v15, v14
	v_div_fmas_f32 v12, v12, v13, v15
	v_div_fixup_f32 v10, v12, v10, v8
	v_pk_mul_f32 v[2:3], v[2:3], v[10:11]
	s_nop 0
	v_cvt_pk_bf16_f32 v7, v2, v3
	v_mov_b64_e32 v[214:215], v[6:7]
	s_nop 1
	v_permlane16_swap_b32_e32 v212, v214
	v_permlane16_swap_b32_e32 v213, v215
	global_store_dwordx4 v[216:217], v[212:215], off

.LBB0_228:
	v_bfe_u32 v210, v220, 4, 1
	v_mul_u32_u24_e32 v210, 24, v210
	v_mov_b32_e32 v211, 0
	s_waitcnt vmcnt(0)
	v_and_b32_e32 v35, 64, v220
	v_xor_b32_e32 v34, 16, v220
	v_add_u32_e32 v35, 64, v35
	v_cmp_lt_i32_e32 vcc, v34, v35
	v_or_b32_e32 v42, s2, v165
	v_lshl_or_b32 v36, v166, 2, s3
	v_cndmask_b32_e32 v34, v220, v34, vcc
	v_lshlrev_b32_e32 v48, 2, v34
	v_xor_b32_e32 v34, 32, v220
	v_cmp_lt_i32_e32 vcc, v34, v35
	v_ashrrev_i32_e32 v43, 31, v42
	v_mov_b32_e32 v37, v9
	v_cndmask_b32_e32 v34, v220, v34, vcc
	v_lshlrev_b32_e32 v45, 2, v34
	ds_bpermute_b32 v34, v48, v134
	s_waitcnt lgkmcnt(0)
	v_add_f32_e32 v34, v134, v34
	ds_bpermute_b32 v35, v45, v34
	s_waitcnt lgkmcnt(0)
	v_add_f32_e32 v34, v34, v35
	v_div_scale_f32 v35, s[0:1], v34, v34, 1.0
	v_rcp_f32_e32 v38, v35
	s_nop 0
	v_fma_f32 v39, -v35, v38, 1.0
	v_fmac_f32_e32 v38, v39, v38
	v_div_scale_f32 v39, vcc, 1.0, v34, 1.0
	v_mul_f32_e32 v40, v39, v38
	v_fma_f32 v41, -v35, v40, v39
	v_fmac_f32_e32 v40, v41, v38
	v_fma_f32 v35, -v35, v40, v39
	v_div_fmas_f32 v35, v35, v38, v40
	v_div_fixup_f32 v44, v35, v34, 1.0
	v_mov_b64_e32 v[34:35], s[70:71]
	v_mad_i64_i32 v[34:35], s[0:1], v42, s77, v[34:35]
	s_mov_b64 s[0:1], 0x1000
	s_nop 0
	v_lshl_add_u64 v[46:47], v[34:35], 0, s[0:1]
	v_readlane_b32 s0, v251, 10
	v_lshlrev_b64 v[34:35], 11, v[42:43]
	v_readlane_b32 s1, v251, 11
	v_readlane_b32 s2, v251, 12
	v_readlane_b32 s3, v251, 13
	s_mov_b64 s[0:1], 0xb00200
	v_pk_mul_f32 v[30:31], v[30:31], v[44:45] op_sel_hi:[1,0]
	v_lshl_add_u64 v[34:35], s[2:3], 0, v[34:35]
	v_lshl_add_u64 v[40:41], v[34:35], 0, s[0:1]
	v_lshlrev_b32_e32 v34, 1, v36
	v_mov_b32_e32 v35, v9
	v_lshl_add_u64 v[38:39], v[46:47], 0, v[34:35]
	v_mov_b64_e32 v[176:177], v[38:39]
	global_load_dwordx2 v[38:39], v[38:39], off
	global_load_dwordx2 v[178:179], v[176:177], off offset:32
	global_load_dwordx2 v[180:181], v[176:177], off offset:64
	global_load_dwordx2 v[182:183], v[176:177], off offset:96
	v_pk_mul_f32 v[32:33], v[32:33], v[44:45] op_sel_hi:[1,0]
	v_pk_mul_f32 v[26:27], v[26:27], v[44:45] op_sel_hi:[1,0]
	v_pk_mul_f32 v[28:29], v[28:29], v[44:45] op_sel_hi:[1,0]
	v_pk_mul_f32 v[4:5], v[4:5], v[44:45] op_sel_hi:[1,0]
	v_pk_mul_f32 v[6:7], v[6:7], v[44:45] op_sel_hi:[1,0]
	v_pk_mul_f32 v[0:1], v[0:1], v[44:45] op_sel_hi:[1,0]
	v_pk_mul_f32 v[2:3], v[2:3], v[44:45] op_sel_hi:[1,0]
	s_waitcnt vmcnt(3)
	v_lshlrev_b32_e32 v43, 16, v38
	v_and_b32_e32 v38, 0xffff0000, v38
	v_mul_f32_e32 v49, 0xbfb8aa3b, v43
	v_exp_f32_e32 v50, v49
	v_mul_f32_e32 v49, 0xbfb8aa3b, v38
	v_exp_f32_e32 v51, v49
	s_nop 0
	v_pk_add_f32 v[50:51], v[50:51], 1.0 op_sel_hi:[1,0]
	s_nop 0
	v_div_scale_f32 v49, s[0:1], v51, v51, v38
	v_rcp_f32_e32 v52, v49
	s_nop 0
	v_fma_f32 v53, -v49, v52, 1.0
	v_fmac_f32_e32 v52, v53, v52
	v_div_scale_f32 v53, vcc, v38, v51, v38
	v_mul_f32_e32 v54, v53, v52
	v_fma_f32 v55, -v49, v54, v53
	v_fmac_f32_e32 v54, v55, v52
	v_fma_f32 v49, -v49, v54, v53
	v_div_fmas_f32 v49, v49, v52, v54
	v_div_fixup_f32 v51, v49, v51, v38
	v_div_scale_f32 v38, s[0:1], v50, v50, v43
	v_rcp_f32_e32 v49, v38
	s_nop 0
	v_fma_f32 v52, -v38, v49, 1.0
	v_fmac_f32_e32 v49, v52, v49
	v_div_scale_f32 v52, vcc, v43, v50, v43
	v_mul_f32_e32 v53, v52, v49
	v_fma_f32 v54, -v38, v53, v52
	v_fmac_f32_e32 v53, v54, v49
	v_fma_f32 v38, -v38, v53, v52
	v_div_fmas_f32 v38, v38, v49, v53
	v_div_fixup_f32 v50, v38, v50, v43
	v_lshlrev_b32_e32 v43, 16, v39
	v_and_b32_e32 v49, 0xffff0000, v39
	v_mul_f32_e32 v38, 0xbfb8aa3b, v43
	v_mul_f32_e32 v39, 0xbfb8aa3b, v49
	v_exp_f32_e32 v38, v38
	v_exp_f32_e32 v39, v39
	v_pk_mul_f32 v[30:31], v[30:31], v[50:51]
	v_pk_add_f32 v[38:39], v[38:39], 1.0 op_sel_hi:[1,0]
	s_nop 0
	v_div_scale_f32 v50, s[0:1], v39, v39, v49
	v_rcp_f32_e32 v51, v50
	v_cvt_pk_bf16_f32 v30, v30, v31
	v_fma_f32 v52, -v50, v51, 1.0
	v_fmac_f32_e32 v51, v52, v51
	v_div_scale_f32 v52, vcc, v49, v39, v49
	v_mul_f32_e32 v53, v52, v51
	v_fma_f32 v54, -v50, v53, v52
	v_fmac_f32_e32 v53, v54, v51
	v_fma_f32 v50, -v50, v53, v52
	v_div_fmas_f32 v50, v50, v51, v53
	v_div_fixup_f32 v39, v50, v39, v49
	v_div_scale_f32 v49, s[0:1], v38, v38, v43
	v_rcp_f32_e32 v50, v49
	s_nop 0
	v_fma_f32 v51, -v49, v50, 1.0
	v_fmac_f32_e32 v50, v51, v50
	v_div_scale_f32 v51, vcc, v43, v38, v43
	v_mul_f32_e32 v52, v51, v50
	v_fma_f32 v53, -v49, v52, v51
	v_fmac_f32_e32 v52, v53, v50
	v_fma_f32 v49, -v49, v52, v51
	v_div_fmas_f32 v49, v49, v50, v52
	v_div_fixup_f32 v38, v49, v38, v43
	v_pk_mul_f32 v[32:33], v[32:33], v[38:39]
	v_or_b32_e32 v38, 16, v36
	v_cvt_pk_bf16_f32 v31, v32, v33
	v_lshl_add_u64 v[32:33], v[40:41], 0, v[34:35]
	v_mov_b64_e32 v[204:205], v[30:31]
	v_lshl_add_u64 v[208:209], v[32:33], 0, v[210:211]
	v_lshlrev_b32_e32 v30, 1, v38
	v_mov_b32_e32 v31, v9
	v_lshl_add_u64 v[32:33], v[46:47], 0, v[30:31]
	s_waitcnt vmcnt(2)
	v_mov_b64_e32 v[32:33], v[178:179]
	v_mov_b32_e32 v39, v9
	s_nop 0
	v_lshlrev_b32_e32 v43, 16, v32
	v_and_b32_e32 v32, 0xffff0000, v32
	v_mul_f32_e32 v34, 0xbfb8aa3b, v43
	v_mul_f32_e32 v35, 0xbfb8aa3b, v32
	v_exp_f32_e32 v34, v34
	v_exp_f32_e32 v35, v35
	s_nop 0
	v_pk_add_f32 v[34:35], v[34:35], 1.0 op_sel_hi:[1,0]
	s_nop 0
	v_div_scale_f32 v49, s[0:1], v35, v35, v32
	v_rcp_f32_e32 v50, v49
	s_nop 0
	v_fma_f32 v51, -v49, v50, 1.0
	v_fmac_f32_e32 v50, v51, v50
	v_div_scale_f32 v51, vcc, v32, v35, v32
	v_mul_f32_e32 v52, v51, v50
	v_fma_f32 v53, -v49, v52, v51
	v_fmac_f32_e32 v52, v53, v50
	v_fma_f32 v49, -v49, v52, v51
	v_div_fmas_f32 v49, v49, v50, v52
	v_div_fixup_f32 v35, v49, v35, v32
	v_div_scale_f32 v32, s[0:1], v34, v34, v43
	v_rcp_f32_e32 v49, v32
	s_nop 0
	v_fma_f32 v50, -v32, v49, 1.0
	v_fmac_f32_e32 v49, v50, v49
	v_div_scale_f32 v50, vcc, v43, v34, v43
	v_mul_f32_e32 v51, v50, v49
	v_fma_f32 v52, -v32, v51, v50
	v_fmac_f32_e32 v51, v52, v49
	v_fma_f32 v32, -v32, v51, v50
	v_div_fmas_f32 v32, v32, v49, v51
	v_div_fixup_f32 v34, v32, v34, v43
	v_pk_mul_f32 v[26:27], v[26:27], v[34:35]
	v_lshlrev_b32_e32 v34, 16, v33
	v_and_b32_e32 v35, 0xffff0000, v33
	v_mul_f32_e32 v32, 0xbfb8aa3b, v34
	v_mul_f32_e32 v33, 0xbfb8aa3b, v35
	v_exp_f32_e32 v32, v32
	v_exp_f32_e32 v33, v33
	v_cvt_pk_bf16_f32 v26, v26, v27
	v_pk_add_f32 v[32:33], v[32:33], 1.0 op_sel_hi:[1,0]
	s_nop 0
	v_div_scale_f32 v43, s[0:1], v33, v33, v35
	v_rcp_f32_e32 v49, v43
	s_nop 0
	v_fma_f32 v50, -v43, v49, 1.0
	v_fmac_f32_e32 v49, v50, v49
	v_div_scale_f32 v50, vcc, v35, v33, v35
	v_mul_f32_e32 v51, v50, v49
	v_fma_f32 v52, -v43, v51, v50
	v_fmac_f32_e32 v51, v52, v49
	v_fma_f32 v43, -v43, v51, v50
	v_div_fmas_f32 v43, v43, v49, v51
	v_div_fixup_f32 v33, v43, v33, v35
	v_div_scale_f32 v35, s[0:1], v32, v32, v34
	v_rcp_f32_e32 v43, v35
	s_nop 0
	v_fma_f32 v49, -v35, v43, 1.0
	v_fmac_f32_e32 v43, v49, v43
	v_div_scale_f32 v49, vcc, v34, v32, v34
	v_mul_f32_e32 v50, v49, v43
	v_fma_f32 v51, -v35, v50, v49
	v_fmac_f32_e32 v50, v51, v43
	v_fma_f32 v35, -v35, v50, v49
	v_div_fmas_f32 v35, v35, v43, v50
	v_div_fixup_f32 v32, v35, v32, v34
	v_pk_mul_f32 v[28:29], v[28:29], v[32:33]
	v_or_b32_e32 v34, 32, v36
	v_cvt_pk_bf16_f32 v27, v28, v29
	v_lshl_add_u64 v[28:29], v[40:41], 0, v[30:31]
	v_mov_b64_e32 v[206:207], v[26:27]
	s_nop 1
	v_permlane16_swap_b32_e32 v204, v206
	v_permlane16_swap_b32_e32 v205, v207
	global_store_dwordx4 v[208:209], v[204:207], off
	v_lshlrev_b32_e32 v26, 1, v34
	v_mov_b32_e32 v27, v9
	v_lshl_add_u64 v[28:29], v[46:47], 0, v[26:27]
	s_waitcnt vmcnt(2)
	v_mov_b64_e32 v[28:29], v[180:181]
	v_mov_b32_e32 v35, v9
	s_nop 0
	v_lshlrev_b32_e32 v32, 16, v28
	v_and_b32_e32 v28, 0xffff0000, v28
	v_mul_f32_e32 v30, 0xbfb8aa3b, v32
	v_mul_f32_e32 v31, 0xbfb8aa3b, v28
	v_exp_f32_e32 v30, v30
	v_exp_f32_e32 v31, v31
	s_nop 0
	v_pk_add_f32 v[30:31], v[30:31], 1.0 op_sel_hi:[1,0]
	s_nop 0
	v_div_scale_f32 v33, s[0:1], v31, v31, v28
	v_rcp_f32_e32 v43, v33
	s_nop 0
	v_fma_f32 v49, -v33, v43, 1.0
	v_fmac_f32_e32 v43, v49, v43
	v_div_scale_f32 v49, vcc, v28, v31, v28
	v_mul_f32_e32 v50, v49, v43
	v_fma_f32 v51, -v33, v50, v49
	v_fmac_f32_e32 v50, v51, v43
	v_fma_f32 v33, -v33, v50, v49
	v_div_fmas_f32 v33, v33, v43, v50
	v_div_fixup_f32 v31, v33, v31, v28
	v_div_scale_f32 v28, s[0:1], v30, v30, v32
	v_rcp_f32_e32 v33, v28
	s_nop 0
	v_fma_f32 v43, -v28, v33, 1.0
	v_fmac_f32_e32 v33, v43, v33
	v_div_scale_f32 v43, vcc, v32, v30, v32
	v_mul_f32_e32 v49, v43, v33
	v_fma_f32 v50, -v28, v49, v43
	v_fmac_f32_e32 v49, v50, v33
	v_fma_f32 v28, -v28, v49, v43
	v_div_fmas_f32 v28, v28, v33, v49
	v_div_fixup_f32 v30, v28, v30, v32
	v_pk_mul_f32 v[4:5], v[4:5], v[30:31]
	v_lshlrev_b32_e32 v30, 16, v29
	v_and_b32_e32 v31, 0xffff0000, v29
	v_mul_f32_e32 v28, 0xbfb8aa3b, v30
	v_mul_f32_e32 v29, 0xbfb8aa3b, v31
	v_exp_f32_e32 v28, v28
	v_exp_f32_e32 v29, v29
	v_cvt_pk_bf16_f32 v4, v4, v5
	v_pk_add_f32 v[28:29], v[28:29], 1.0 op_sel_hi:[1,0]
	s_nop 0
	v_div_scale_f32 v32, s[0:1], v29, v29, v31
	v_rcp_f32_e32 v33, v32
	s_nop 0
	v_fma_f32 v43, -v32, v33, 1.0
	v_fmac_f32_e32 v33, v43, v33
	v_div_scale_f32 v43, vcc, v31, v29, v31
	v_mul_f32_e32 v49, v43, v33
	v_fma_f32 v50, -v32, v49, v43
	v_fmac_f32_e32 v49, v50, v33
	v_fma_f32 v32, -v32, v49, v43
	v_div_fmas_f32 v32, v32, v33, v49
	v_div_fixup_f32 v29, v32, v29, v31
	v_div_scale_f32 v31, s[0:1], v28, v28, v30
	v_rcp_f32_e32 v32, v31
	s_nop 0
	v_fma_f32 v33, -v31, v32, 1.0
	v_fmac_f32_e32 v32, v33, v32
	v_div_scale_f32 v33, vcc, v30, v28, v30
	v_mul_f32_e32 v43, v33, v32
	v_fma_f32 v49, -v31, v43, v33
	v_fmac_f32_e32 v43, v49, v32
	v_fma_f32 v31, -v31, v43, v33
	v_div_fmas_f32 v31, v31, v32, v43
	v_div_fixup_f32 v28, v31, v28, v30
	v_pk_mul_f32 v[6:7], v[6:7], v[28:29]
	s_nop 0
	v_cvt_pk_bf16_f32 v5, v6, v7
	v_lshl_add_u64 v[6:7], v[40:41], 0, v[26:27]
	v_mov_b64_e32 v[212:213], v[4:5]
	v_lshl_add_u64 v[216:217], v[6:7], 0, v[210:211]
	v_or_b32_e32 v4, 48, v36
	v_lshlrev_b32_e32 v6, 1, v4
	v_mov_b32_e32 v7, v9
	v_lshl_add_u64 v[26:27], v[46:47], 0, v[6:7]
	s_waitcnt vmcnt(1)
	v_mov_b64_e32 v[26:27], v[182:183]
	v_mov_b32_e32 v5, v9
	s_nop 0
	v_lshlrev_b32_e32 v30, 16, v26
	v_and_b32_e32 v26, 0xffff0000, v26
	v_mul_f32_e32 v28, 0xbfb8aa3b, v30
	v_mul_f32_e32 v29, 0xbfb8aa3b, v26
	v_exp_f32_e32 v28, v28
	v_exp_f32_e32 v29, v29
	s_nop 0
	v_pk_add_f32 v[28:29], v[28:29], 1.0 op_sel_hi:[1,0]
	s_nop 0
	v_div_scale_f32 v31, s[0:1], v29, v29, v26
	v_rcp_f32_e32 v32, v31
	s_nop 0
	v_fma_f32 v33, -v31, v32, 1.0
	v_fmac_f32_e32 v32, v33, v32
	v_div_scale_f32 v33, vcc, v26, v29, v26
	v_mul_f32_e32 v43, v33, v32
	v_fma_f32 v46, -v31, v43, v33
	v_fmac_f32_e32 v43, v46, v32
	v_fma_f32 v31, -v31, v43, v33
	v_div_fmas_f32 v31, v31, v32, v43
	v_div_fixup_f32 v29, v31, v29, v26
	v_div_scale_f32 v26, s[0:1], v28, v28, v30
	v_rcp_f32_e32 v31, v26
	s_nop 0
	v_fma_f32 v32, -v26, v31, 1.0
	v_fmac_f32_e32 v31, v32, v31
	v_div_scale_f32 v32, vcc, v30, v28, v30
	v_mul_f32_e32 v33, v32, v31
	v_fma_f32 v43, -v26, v33, v32
	v_fmac_f32_e32 v33, v43, v31
	v_fma_f32 v26, -v26, v33, v32
	v_div_fmas_f32 v26, v26, v31, v33
	v_div_fixup_f32 v28, v26, v28, v30
	v_pk_mul_f32 v[0:1], v[0:1], v[28:29]
	v_lshlrev_b32_e32 v28, 16, v27
	v_and_b32_e32 v29, 0xffff0000, v27
	v_mul_f32_e32 v26, 0xbfb8aa3b, v28
	v_mul_f32_e32 v27, 0xbfb8aa3b, v29
	v_exp_f32_e32 v26, v26
	v_exp_f32_e32 v27, v27
	v_cvt_pk_bf16_f32 v0, v0, v1
	v_pk_add_f32 v[26:27], v[26:27], 1.0 op_sel_hi:[1,0]
	s_nop 0
	v_div_scale_f32 v30, s[0:1], v27, v27, v29
	v_rcp_f32_e32 v31, v30
	s_nop 0
	v_fma_f32 v32, -v30, v31, 1.0
	v_fmac_f32_e32 v31, v32, v31
	v_div_scale_f32 v32, vcc, v29, v27, v29
	v_mul_f32_e32 v33, v32, v31
	v_fma_f32 v43, -v30, v33, v32
	v_fmac_f32_e32 v33, v43, v31
	v_fma_f32 v30, -v30, v33, v32
	v_div_fmas_f32 v30, v30, v31, v33
	v_div_fixup_f32 v27, v30, v27, v29
	v_div_scale_f32 v29, s[0:1], v26, v26, v28
	v_rcp_f32_e32 v30, v29
	s_mov_b64 s[0:1], 0
	v_fma_f32 v31, -v29, v30, 1.0
	v_fmac_f32_e32 v30, v31, v30
	v_div_scale_f32 v31, vcc, v28, v26, v28
	v_mul_f32_e32 v32, v31, v30
	v_fma_f32 v33, -v29, v32, v31
	v_fmac_f32_e32 v32, v33, v30
	v_fma_f32 v29, -v29, v32, v31
	v_div_fmas_f32 v29, v29, v30, v32
	v_div_fixup_f32 v26, v29, v26, v28
	v_pk_mul_f32 v[2:3], v[2:3], v[26:27]
	s_nop 0
	v_cvt_pk_bf16_f32 v1, v2, v3
	v_lshl_add_u64 v[2:3], v[40:41], 0, v[6:7]
	v_mov_b64_e32 v[214:215], v[0:1]
	s_nop 1
	v_permlane16_swap_b32_e32 v212, v214
	v_permlane16_swap_b32_e32 v213, v215
	global_store_dwordx4 v[216:217], v[212:215], off
	ds_bpermute_b32 v0, v48, v135
	s_waitcnt lgkmcnt(0)
	v_add_f32_e32 v0, v135, v0
	ds_bpermute_b32 v1, v45, v0
